# v44 plus: first-barrier census issues its 16 per-XCC counter loads back to back with one wait instead of a wait after each
# speedup vs baseline: 1.0180x; 1.0023x over previous
.LBB0_533:
	v_readlane_b32 s6, v252, 61
	v_readlane_b32 s7, v252, 62
	s_waitcnt lgkmcnt(0)
	global_load_dword v0, v169, s[36:37] sc1
	v_readlane_b32 s8, v254, 7
	s_nop 1
	global_load_dword v1, v169, s[6:7] sc1
	v_readlane_b32 s6, v252, 63
	v_readlane_b32 s7, v253, 0
	s_nop 1
	s_nop 2
	global_load_dword v2, v169, s[6:7] sc1
	v_readlane_b32 s6, v253, 1
	v_readlane_b32 s7, v253, 2
	s_nop 1
	s_nop 2
	global_load_dword v3, v169, s[6:7] sc1
	v_readlane_b32 s6, v253, 3
	v_readlane_b32 s7, v253, 4
	s_nop 1
	s_nop 2
	global_load_dword v4, v169, s[6:7] sc1
	v_readlane_b32 s6, v253, 5
	v_readlane_b32 s7, v253, 6
	s_nop 1
	s_nop 2
	global_load_dword v5, v169, s[6:7] sc1
	v_readlane_b32 s6, v253, 7
	v_readlane_b32 s7, v253, 8
	s_nop 1
	s_nop 2
	global_load_dword v6, v169, s[6:7] sc1
	v_readlane_b32 s6, v253, 9
	v_readlane_b32 s7, v253, 10
	s_nop 1
	s_nop 2
	global_load_dword v7, v169, s[6:7] sc1
	v_readlane_b32 s6, v253, 11
	v_readlane_b32 s7, v253, 12
	s_nop 1
	s_nop 2
	global_load_dword v8, v169, s[6:7] sc1
	v_readlane_b32 s6, v253, 13
	v_readlane_b32 s7, v253, 14
	s_nop 1
	s_nop 2
	global_load_dword v9, v169, s[6:7] sc1
	v_readlane_b32 s6, v253, 15
	v_readlane_b32 s7, v253, 16
	s_nop 1
	s_nop 2
	global_load_dword v10, v169, s[6:7] sc1
	v_readlane_b32 s6, v253, 17
	v_readlane_b32 s7, v253, 18
	s_nop 1
	s_nop 2
	global_load_dword v11, v169, s[6:7] sc1
	v_readlane_b32 s6, v253, 19
	v_readlane_b32 s7, v253, 20
	s_nop 1
	s_nop 2
	global_load_dword v12, v169, s[6:7] sc1
	v_readlane_b32 s6, v253, 21
	v_readlane_b32 s7, v253, 22
	s_nop 1
	s_nop 2
	global_load_dword v13, v169, s[6:7] sc1
	v_readlane_b32 s6, v253, 23
	v_readlane_b32 s7, v253, 24
	s_nop 1
	s_nop 2
	global_load_dword v14, v169, s[6:7] sc1
	v_readlane_b32 s6, v253, 25
	v_readlane_b32 s7, v253, 26
	s_nop 1
	s_nop 2
	global_load_dword v15, v169, s[6:7] sc1
	s_mov_b64 s[6:7], -1
	s_waitcnt vmcnt(0)
	v_add_u32_e32 v16, v1, v0
	v_add_u32_e32 v16, v16, v2
	v_add_u32_e32 v16, v16, v3
	v_add_u32_e32 v16, v16, v4
	v_add_u32_e32 v16, v16, v5
	v_add_u32_e32 v16, v16, v6
	v_add_u32_e32 v16, v16, v7
	v_add_u32_e32 v16, v16, v8
	v_add_u32_e32 v16, v16, v9
	v_add_u32_e32 v16, v16, v10
	v_add_u32_e32 v16, v16, v11
	v_add_u32_e32 v16, v16, v12
	v_add_u32_e32 v16, v16, v13
	v_add_u32_e32 v16, v16, v14
	v_add_u32_e32 v16, v16, v15
	v_cmp_eq_u32_e32 vcc, s8, v16
	s_mov_b64 s[8:9], -1
	s_cbranch_vccnz .LBB0_532
	s_and_b32 s6, s11, 0xff
	s_cmp_eq_u32 s6, 0
	s_mov_b64 s[6:7], -1
	s_mov_b64 s[16:17], -1
	s_sleep 1
	s_cbranch_scc1 .LBB0_537
	s_and_b64 vcc, exec, s[16:17]
	s_cbranch_vccz .LBB0_532
